# v14 plus: the three ranks' partial loads in the MoBA home combine issued together (sc1), one wait
# baseline (speedup 1.0000x reference)
.LBB0_1962:
	s_waitcnt vmcnt(0)
	s_waitcnt lgkmcnt(0)
	s_barrier
	s_waitcnt vmcnt(7)
	v_mov_b32_e32 v2, v170
	v_mov_b32_e32 v3, v14
	s_waitcnt vmcnt(0)
	s_nop 0
	v_permlane32_swap_b32_e32 v14, v3
	v_lshl_add_u32 v4, v2, 1, v2
	v_add_f32_e32 v3, v14, v3
	v_cmp_ne_u32_sdwa s[20:21], v179, v167 src0_sel:BYTE_0 src1_sel:DWORD
	v_ashrrev_i32_e32 v5, 31, v4
	v_and_b32_e32 v6, 0xff00, v179
	v_cmp_ne_u32_e64 s[22:23], 0, v6
	v_and_b32_e32 v7, 0xff0000, v179
	v_cmp_ne_u32_e64 s[24:25], 0, v7
	s_mov_b64 s[18:19], exec
	v_lshlrev_b64 v[14:15], 2, v[4:5]
	v_lshlrev_b64 v[6:7], 8, v[4:5]
	v_lshl_add_u64 v[126:127], s[48:49], 0, v[14:15]
	v_lshl_add_u64 v[128:129], s[46:47], 0, v[14:15]
	v_lshl_add_u64 v[4:5], v[172:173], 0, v[6:7]
	s_and_b64 exec, s[18:19], s[20:21]
	global_load_dword v88, v[126:127], off sc1
	global_load_dwordx4 v[6:9], v[4:5], off sc1
	global_load_dwordx4 v[10:13], v[4:5], off offset:128 sc1
	global_load_dwordx4 v[64:67], v[4:5], off offset:32 sc1
	global_load_dwordx4 v[68:71], v[4:5], off offset:160 sc1
	global_load_dwordx4 v[72:75], v[4:5], off offset:64 sc1
	global_load_dwordx4 v[76:79], v[4:5], off offset:192 sc1
	global_load_dwordx4 v[80:83], v[4:5], off offset:96 sc1
	global_load_dwordx4 v[84:87], v[4:5], off offset:224 sc1
	global_load_dword v15, v[128:129], off sc1
	s_and_b64 exec, s[18:19], s[22:23]
	global_load_dword v114, v[126:127], off offset:4 sc1
	global_load_dwordx4 v[90:93], v[4:5], off offset:256 sc1
	global_load_dwordx4 v[94:97], v[4:5], off offset:384 sc1
	global_load_dwordx4 v[98:101], v[4:5], off offset:288 sc1
	global_load_dwordx4 v[102:105], v[4:5], off offset:416 sc1
	global_load_dwordx4 v[106:109], v[4:5], off offset:320 sc1
	global_load_dwordx4 v[110:113], v[4:5], off offset:448 sc1
	global_load_dwordx4 v[116:119], v[4:5], off offset:352 sc1
	global_load_dwordx4 v[120:123], v[4:5], off offset:480 sc1
	global_load_dword v125, v[128:129], off offset:4 sc1
	s_and_b64 exec, s[18:19], s[24:25]
	global_load_dword v89, v[126:127], off offset:8 sc1
	global_load_dwordx4 v[130:133], v[4:5], off offset:512 sc1
	global_load_dwordx4 v[134:137], v[4:5], off offset:640 sc1
	global_load_dwordx4 v[138:141], v[4:5], off offset:544 sc1
	global_load_dwordx4 v[142:145], v[4:5], off offset:672 sc1
	global_load_dwordx4 v[146:149], v[4:5], off offset:576 sc1
	global_load_dwordx4 v[150:153], v[4:5], off offset:704 sc1
	global_load_dwordx4 v[154:157], v[4:5], off offset:608 sc1
	global_load_dwordx4 v[158:161], v[4:5], off offset:736 sc1
	global_load_dword v163, v[128:129], off offset:8 sc1
	s_mov_b64 exec, s[18:19]
	s_waitcnt vmcnt(0)
	s_and_b64 exec, s[18:19], s[20:21]
	v_sub_f32_e32 v14, v88, v1
	v_exp_f32_e32 v14, v14
	s_nop 0
	v_pk_fma_f32 v[48:49], v[6:7], v[14:15], v[48:49] op_sel_hi:[1,0,1]
	v_pk_fma_f32 v[50:51], v[8:9], v[14:15], v[50:51] op_sel_hi:[1,0,1]
	v_pk_fma_f32 v[32:33], v[10:11], v[14:15], v[32:33] op_sel_hi:[1,0,1]
	v_pk_fma_f32 v[34:35], v[12:13], v[14:15], v[34:35] op_sel_hi:[1,0,1]
	v_pk_fma_f32 v[52:53], v[64:65], v[14:15], v[52:53] op_sel_hi:[1,0,1]
	v_pk_fma_f32 v[54:55], v[66:67], v[14:15], v[54:55] op_sel_hi:[1,0,1]
	v_pk_fma_f32 v[36:37], v[68:69], v[14:15], v[36:37] op_sel_hi:[1,0,1]
	v_pk_fma_f32 v[38:39], v[70:71], v[14:15], v[38:39] op_sel_hi:[1,0,1]
	v_pk_fma_f32 v[56:57], v[72:73], v[14:15], v[56:57] op_sel_hi:[1,0,1]
	v_pk_fma_f32 v[58:59], v[74:75], v[14:15], v[58:59] op_sel_hi:[1,0,1]
	v_pk_fma_f32 v[40:41], v[76:77], v[14:15], v[40:41] op_sel_hi:[1,0,1]
	v_pk_fma_f32 v[42:43], v[78:79], v[14:15], v[42:43] op_sel_hi:[1,0,1]
	v_pk_fma_f32 v[60:61], v[80:81], v[14:15], v[60:61] op_sel_hi:[1,0,1]
	v_pk_fma_f32 v[62:63], v[82:83], v[14:15], v[62:63] op_sel_hi:[1,0,1]
	v_pk_fma_f32 v[44:45], v[84:85], v[14:15], v[44:45] op_sel_hi:[1,0,1]
	v_pk_fma_f32 v[46:47], v[86:87], v[14:15], v[46:47] op_sel_hi:[1,0,1]
	v_fmac_f32_e32 v3, v14, v15
	s_and_b64 exec, s[18:19], s[22:23]
	v_sub_f32_e32 v124, v114, v1
	v_exp_f32_e32 v124, v124
	s_nop 0
	v_pk_fma_f32 v[48:49], v[90:91], v[124:125], v[48:49] op_sel_hi:[1,0,1]
	v_pk_fma_f32 v[50:51], v[92:93], v[124:125], v[50:51] op_sel_hi:[1,0,1]
	v_pk_fma_f32 v[32:33], v[94:95], v[124:125], v[32:33] op_sel_hi:[1,0,1]
	v_pk_fma_f32 v[34:35], v[96:97], v[124:125], v[34:35] op_sel_hi:[1,0,1]
	v_pk_fma_f32 v[52:53], v[98:99], v[124:125], v[52:53] op_sel_hi:[1,0,1]
	v_pk_fma_f32 v[54:55], v[100:101], v[124:125], v[54:55] op_sel_hi:[1,0,1]
	v_pk_fma_f32 v[36:37], v[102:103], v[124:125], v[36:37] op_sel_hi:[1,0,1]
	v_pk_fma_f32 v[38:39], v[104:105], v[124:125], v[38:39] op_sel_hi:[1,0,1]
	v_pk_fma_f32 v[56:57], v[106:107], v[124:125], v[56:57] op_sel_hi:[1,0,1]
	v_pk_fma_f32 v[58:59], v[108:109], v[124:125], v[58:59] op_sel_hi:[1,0,1]
	v_pk_fma_f32 v[40:41], v[110:111], v[124:125], v[40:41] op_sel_hi:[1,0,1]
	v_pk_fma_f32 v[42:43], v[112:113], v[124:125], v[42:43] op_sel_hi:[1,0,1]
	v_pk_fma_f32 v[60:61], v[116:117], v[124:125], v[60:61] op_sel_hi:[1,0,1]
	v_pk_fma_f32 v[62:63], v[118:119], v[124:125], v[62:63] op_sel_hi:[1,0,1]
	v_pk_fma_f32 v[44:45], v[120:121], v[124:125], v[44:45] op_sel_hi:[1,0,1]
	v_pk_fma_f32 v[46:47], v[122:123], v[124:125], v[46:47] op_sel_hi:[1,0,1]
	v_fmac_f32_e32 v3, v124, v125
	s_and_b64 exec, s[18:19], s[24:25]
	v_sub_f32_e32 v162, v89, v1
	v_exp_f32_e32 v162, v162
	s_nop 0
	v_pk_fma_f32 v[48:49], v[130:131], v[162:163], v[48:49] op_sel_hi:[1,0,1]
	v_pk_fma_f32 v[50:51], v[132:133], v[162:163], v[50:51] op_sel_hi:[1,0,1]
	v_pk_fma_f32 v[32:33], v[134:135], v[162:163], v[32:33] op_sel_hi:[1,0,1]
	v_pk_fma_f32 v[34:35], v[136:137], v[162:163], v[34:35] op_sel_hi:[1,0,1]
	v_pk_fma_f32 v[52:53], v[138:139], v[162:163], v[52:53] op_sel_hi:[1,0,1]
	v_pk_fma_f32 v[54:55], v[140:141], v[162:163], v[54:55] op_sel_hi:[1,0,1]
	v_pk_fma_f32 v[36:37], v[142:143], v[162:163], v[36:37] op_sel_hi:[1,0,1]
	v_pk_fma_f32 v[38:39], v[144:145], v[162:163], v[38:39] op_sel_hi:[1,0,1]
	v_pk_fma_f32 v[56:57], v[146:147], v[162:163], v[56:57] op_sel_hi:[1,0,1]
	v_pk_fma_f32 v[58:59], v[148:149], v[162:163], v[58:59] op_sel_hi:[1,0,1]
	v_pk_fma_f32 v[40:41], v[150:151], v[162:163], v[40:41] op_sel_hi:[1,0,1]
	v_pk_fma_f32 v[42:43], v[152:153], v[162:163], v[42:43] op_sel_hi:[1,0,1]
	v_pk_fma_f32 v[60:61], v[154:155], v[162:163], v[60:61] op_sel_hi:[1,0,1]
	v_pk_fma_f32 v[62:63], v[156:157], v[162:163], v[62:63] op_sel_hi:[1,0,1]
	v_pk_fma_f32 v[44:45], v[158:159], v[162:163], v[44:45] op_sel_hi:[1,0,1]
	v_pk_fma_f32 v[46:47], v[160:161], v[162:163], v[46:47] op_sel_hi:[1,0,1]
	v_fmac_f32_e32 v3, v162, v163
	s_mov_b64 exec, s[18:19]
	s_branch .LBB0_1872
